# unit-start barriers no longer wait for the previous unit's O stores (entry wait moved to phase preheader)
# speedup vs baseline: 1.0007x; 1.0007x over previous
.LBB0_554:
	s_cmpk_gt_i32 s17, 0x1ff
	s_cbranch_scc1 .LBB0_563
	s_add_u32 s4, s26, 0x1a300000
	s_addc_u32 s5, s27, 0
	s_add_u32 s0, s26, 0xe200900
	v_mbcnt_lo_u32_b32 v0, -1, 0
	s_addc_u32 s1, s27, 0
	v_mbcnt_hi_u32_b32 v192, -1, v0
	s_add_u32 s12, s26, 0x4400000
	v_and_b32_e32 v0, 64, v192
	s_addc_u32 s13, s27, 0
	s_mov_b32 s7, 0
	s_movk_i32 s14, 0xc00
	v_mov_b64_e32 v[168:169], s[0:1]
	v_mov_b32_e32 v171, 0
	s_mov_b64 s[8:9], 0x18000
	s_mov_b32 s15, 0x18000
	v_mov_b32_e32 v177, 0xff
	s_movk_i32 s18, 0x90
	s_mov_b32 s19, 0xf0c9f2ca
	s_mov_b32 s20, 0x3e38aa3b
	s_movk_i32 s21, 0x4800
	v_xor_b32_e32 v193, 32, v192
	v_add_u32_e32 v194, 64, v0
	s_waitcnt vmcnt(0)
	s_branch .LBB0_557

.LBB0_557:
	s_ashr_i32 s0, s17, 4
	s_ashr_i32 s1, s0, 31
	s_lshl_b64 s[2:3], s[0:1], 19
	s_add_u32 s2, s12, s2
	s_addc_u32 s3, s13, s3
	s_lshl_b32 s6, s17, 4
	s_and_b32 s34, s6, 0xc0
	s_lshl_b32 s6, s34, 1
	s_add_u32 s2, s2, s6
	v_mov_b32_e32 v44, v200
	s_addc_u32 s3, s3, 0
	s_lshl_b32 s10, s17, 9
	s_and_b32 s10, s10, 0x600
	v_and_b32_e32 v0, 0xffffffc0, v44
	v_and_b32_e32 v45, 31, v44
	v_add_u32_e32 v0, s10, v0
	v_or_b32_e32 v0, v0, v45
	s_lshl_b64 s[0:1], s[0:1], 11
	v_ashrrev_i32_e32 v1, 31, v0
	v_lshl_add_u64 v[172:173], s[0:1], 0, v[0:1]
	v_mad_u64_u32 v[0:1], s[0:1], v172, s14, v[168:169]
	v_bfe_u32 v195, v44, 5, 1
	v_mad_i32_i24 v1, v173, s14, v1
	v_lshl_add_u64 v[0:1], v[0:1], 0, s[6:7]
	v_lshlrev_b32_e32 v170, 4, v195
	v_lshl_add_u64 v[32:33], v[0:1], 0, v[170:171]
	v_add_co_u32_e32 v36, vcc, s15, v32
	v_ashrrev_i32_e32 v198, 3, v44
	s_waitcnt lgkmcnt(0)
	s_barrier
	v_lshl_add_u64 v[34:35], v[32:33], 0, s[8:9]
	v_addc_co_u32_e32 v37, vcc, 0, v33, vcc
	global_load_dwordx4 v[0:3], v[32:33], off
	global_load_dwordx4 v[4:7], v[32:33], off offset:32
	global_load_dwordx4 v[8:11], v[34:35], off offset:32
	global_load_dwordx4 v[12:15], v[34:35], off offset:64
	global_load_dwordx4 v[16:19], v[32:33], off offset:64
	global_load_dwordx4 v[20:23], v[32:33], off offset:96
	global_load_dwordx4 v[24:27], v[36:37], off
	global_load_dwordx4 v[28:31], v[34:35], off offset:96
	v_med3_i32 v32, v198, 0, v177
	v_lshlrev_b32_e32 v32, 11, v32
	v_mov_b32_e32 v33, v171
	v_lshlrev_b32_e32 v34, 4, v44
	v_lshl_add_u64 v[32:33], s[2:3], 0, v[32:33]
	v_and_b32_e32 v40, 0x70, v34
	v_mov_b32_e32 v41, v171
	v_lshl_add_u64 v[42:43], v[32:33], 0, v[40:41]
	global_load_dwordx4 v[32:35], v[42:43], off
	global_load_dwordx4 v[36:39], v[42:43], off offset:512
	v_cmp_lt_i32_e32 vcc, v193, v194
	v_lshlrev_b32_e32 v43, 7, v44
	v_and_b32_e32 v43, 0xffffe000, v43
	v_cndmask_b32_e32 v42, v192, v193, vcc
	v_lshlrev_b32_e32 v196, 2, v42
	v_and_b32_e32 v42, 63, v44
	v_lshlrev_b32_e32 v42, 4, v42
	v_mul_lo_u32 v48, v198, s18
	v_add3_u32 v42, 0, v43, v42
	v_add3_u32 v176, 0, v48, v40
	v_mad_u64_u32 v[178:179], s[0:1], v198, 48, v[176:177]
	v_and_b32_e32 v46, 16, v44
	v_bfe_u32 v47, v44, 2, 2
	v_lshlrev_b32_e32 v44, 2, v44
	v_lshl_or_b32 v47, v195, 2, v47
	v_and_or_b32 v44, v44, 12, v46
	v_mul_u32_u24_e32 v45, 0x90, v45
	v_mul_u32_u24_e32 v43, 0xc0, v47
	v_add3_u32 v199, 0, v45, v170
	v_lshl_add_u64 v[180:181], s[2:3], 0, v[40:41]
	v_mov_b32_e32 v170, v171
	v_mov_b32_e32 v201, 0xf149f2ca
	s_mov_b32 s0, 64
	v_mov_b32_e32 v202, 0xf149f2ca
	s_mov_b32 s1, 0
	v_mov_b64_e32 v[174:175], v[170:171]
	s_waitcnt vmcnt(9)
	ds_write_b128 v42, v[0:3] offset:53248
	s_waitcnt vmcnt(8)
	ds_write_b128 v42, v[4:7] offset:54272
	s_waitcnt vmcnt(5)
	ds_write_b128 v42, v[16:19] offset:55296
	s_waitcnt vmcnt(4)
	ds_write_b128 v42, v[20:23] offset:56320
	s_waitcnt vmcnt(3)
	ds_write_b128 v42, v[24:27] offset:57344
	ds_write_b128 v42, v[8:11] offset:58368
	ds_write_b128 v42, v[12:15] offset:59392
	s_waitcnt vmcnt(2)
	ds_write_b128 v42, v[28:31] offset:60416
	s_waitcnt lgkmcnt(0)
	s_barrier
	s_waitcnt vmcnt(1)
	ds_write_b128 v176, v[32:35]
	s_waitcnt vmcnt(0)
	ds_write_b128 v178, v[36:39] offset:18432
	s_waitcnt lgkmcnt(0)
	s_barrier
	ds_read_b128 v[152:155], v42 offset:53248
	ds_read_b128 v[144:147], v42 offset:54272
	ds_read_b128 v[156:159], v42 offset:57344
	ds_read_b128 v[148:151], v42 offset:58368
	ds_read_b128 v[140:143], v42 offset:55296
	ds_read_b128 v[136:139], v42 offset:56320
	ds_read_b128 v[132:135], v42 offset:59392
	ds_read_b128 v[128:131], v42 offset:60416
	v_lshlrev_b32_e32 v0, 1, v44
	v_mov_b32_e32 v14, v171
	v_mov_b32_e32 v15, v171
	v_add3_u32 v179, 0, v43, v0
	v_mov_b32_e32 v0, v171
	v_mov_b32_e32 v1, v171
	v_mov_b32_e32 v2, v171
	v_mov_b32_e32 v3, v171
	v_mov_b32_e32 v4, v171
	v_mov_b32_e32 v5, v171
	v_mov_b32_e32 v6, v171
	v_mov_b32_e32 v7, v171
	v_mov_b32_e32 v8, v171
	v_mov_b32_e32 v9, v171
	v_mov_b32_e32 v10, v171
	v_mov_b32_e32 v11, v171
	v_mov_b32_e32 v12, v171
	v_mov_b32_e32 v13, v171
	v_mov_b64_e32 v[46:47], v[14:15]
	v_mov_b64_e32 v[62:63], v[14:15]
	v_mov_b64_e32 v[30:31], v[14:15]
	v_mov_b64_e32 v[44:45], v[12:13]
	v_mov_b64_e32 v[42:43], v[10:11]
	v_mov_b64_e32 v[40:41], v[8:9]
	v_mov_b64_e32 v[38:39], v[6:7]
	v_mov_b64_e32 v[36:37], v[4:5]
	v_mov_b64_e32 v[34:35], v[2:3]
	v_mov_b64_e32 v[32:33], v[0:1]
	v_mov_b64_e32 v[60:61], v[12:13]
	v_mov_b64_e32 v[58:59], v[10:11]
	v_mov_b64_e32 v[56:57], v[8:9]
	v_mov_b64_e32 v[54:55], v[6:7]
	v_mov_b64_e32 v[52:53], v[4:5]
	v_mov_b64_e32 v[50:51], v[2:3]
	v_mov_b64_e32 v[48:49], v[0:1]
	v_mov_b64_e32 v[28:29], v[12:13]
	v_mov_b64_e32 v[26:27], v[10:11]
	v_mov_b64_e32 v[24:25], v[8:9]
	v_mov_b64_e32 v[22:23], v[6:7]
	v_mov_b64_e32 v[20:21], v[4:5]
	v_mov_b64_e32 v[18:19], v[2:3]
	v_mov_b64_e32 v[16:17], v[0:1]
	s_branch .LBB0_559

.LBB0_621:
	s_add_u32 s12, s26, 0xe200000
	s_addc_u32 s13, s27, 0
	s_add_u32 s14, s26, 0x1a300000
	s_addc_u32 s15, s27, 0
	s_add_u32 s18, s26, 0x5e10000
	s_addc_u32 s19, s27, 0
	s_abs_i32 s62, s30
	v_cvt_f32_u32_e32 v0, s62
	s_sub_i32 s0, 0, s62
	s_movk_i32 s63, 0x104
	s_mov_b32 s64, 0x7e07e07f
	v_rcp_iflag_f32_e32 v0, v0
	s_movk_i32 s65, 0x82
	s_movk_i32 s66, 0xfdf8
	s_mov_b32 s67, 0x20000
	v_mul_f32_e32 v0, 0x4f7ffffe, v0
	v_cvt_u32_f32_e32 v0, v0
	s_movk_i32 s68, 0x200
	s_ashr_i32 s69, s30, 31
	s_movk_i32 s71, 0xff03
	v_readfirstlane_b32 s1, v0
	s_mul_i32 s0, s0, s1
	s_mul_hi_u32 s0, s1, s0
	v_mbcnt_lo_u32_b32 v0, -1, 0
	s_add_i32 s70, s1, s0
	s_movk_i32 s72, 0x210
	v_mov_b32_e32 v1, 0
	s_movk_i32 s73, 0xc00
	v_mov_b64_e32 v[138:139], s[12:13]
	s_mov_b64 s[20:21], 0x18000
	s_mov_b32 s74, 0x18000
	v_mov_b32_e32 v141, 0x7ff
	s_movk_i32 s75, 0x90
	v_mov_b32_e32 v170, 0xc0
	v_mov_b32_e32 v171, 0x100
	s_mov_b32 s76, 0xf0c9f2ca
	s_mov_b32 s77, 0x3e38aa3b
	s_movk_i32 s78, 0x4800
	s_movk_i32 s79, 0x201
	v_mov_b32_e32 v172, 0x10000
	v_mov_b32_e32 v173, 0xf149f2ca
	v_mbcnt_hi_u32_b32 v174, -1, v0
	s_waitcnt vmcnt(0)
	s_branch .LBB0_623

.LBB0_626:
	v_mov_b32_e32 v2, v200
	s_waitcnt lgkmcnt(0)
	v_cmp_gt_i32_e32 vcc, s63, v2
	s_barrier
	s_cmp_eq_u64 s[2:3], 0
	s_cbranch_scc1 .Lnsa2_skipfill
	v_add_u32_e32 v206, 0, v200
	v_min_u32_e32 v206, 1407, v206
	v_cmp_lt_u32_e32 vcc, 703, v206
	v_mov_b32_e32 v213, 0
	s_nop 0
	v_cndmask_b32_e64 v207, 0, 1, vcc
	v_mul_u32_u24_e32 v208, 704, v207
	v_sub_u32_e32 v208, v206, v208
	v_subrev_u32_e32 v209, 96, v208
	v_max_i32_e32 v210, 0, v209
	v_min_i32_e32 v210, 0x80, v210
	v_lshlrev_b32_e32 v210, 2, v210
	v_add_u32_e32 v210, 0x20004, v210
	ds_read_b32 v210, v210
	v_mul_u32_u24_e32 v211, 0xb00, v207
	v_lshl_add_u32 v211, v208, 2, v211
	v_add_u32_e32 v211, 0x1d000, v211
	v_add_u32_e32 v218, 512, v200
	v_min_u32_e32 v218, 1407, v218
	v_cmp_lt_u32_e32 vcc, 703, v218
	v_mov_b32_e32 v225, 0
	s_nop 0
	v_cndmask_b32_e64 v219, 0, 1, vcc
	v_mul_u32_u24_e32 v220, 704, v219
	v_sub_u32_e32 v220, v218, v220
	v_subrev_u32_e32 v221, 96, v220
	v_max_i32_e32 v222, 0, v221
	v_min_i32_e32 v222, 0x80, v222
	v_lshlrev_b32_e32 v222, 2, v222
	v_add_u32_e32 v222, 0x20004, v222
	ds_read_b32 v222, v222
	v_mul_u32_u24_e32 v223, 0xb00, v219
	v_lshl_add_u32 v223, v220, 2, v223
	v_add_u32_e32 v223, 0x1d000, v223
	v_add_u32_e32 v230, 1024, v200
	v_min_u32_e32 v230, 1407, v230
	v_cmp_lt_u32_e32 vcc, 703, v230
	v_mov_b32_e32 v237, 0
	s_nop 0
	v_cndmask_b32_e64 v231, 0, 1, vcc
	v_mul_u32_u24_e32 v232, 704, v231
	v_sub_u32_e32 v232, v230, v232
	v_subrev_u32_e32 v233, 96, v232
	v_max_i32_e32 v234, 0, v233
	v_min_i32_e32 v234, 0x80, v234
	v_lshlrev_b32_e32 v234, 2, v234
	v_add_u32_e32 v234, 0x20004, v234
	ds_read_b32 v234, v234
	v_mul_u32_u24_e32 v235, 0xb00, v231
	v_lshl_add_u32 v235, v232, 2, v235
	v_add_u32_e32 v235, 0x1d000, v235
	s_waitcnt lgkmcnt(0)
	v_mul_lo_u32 v210, v210, 12
	v_add3_u32 v212, v210, v207, s81
	v_ashrrev_i32_e32 v213, 31, v212
	v_lshl_add_u64 v[212:213], v[212:213], 2, s[56:57]
	global_load_dword v214, v[212:213], off
	v_mul_lo_u32 v222, v222, 12
	v_add3_u32 v224, v222, v219, s81
	v_ashrrev_i32_e32 v225, 31, v224
	v_lshl_add_u64 v[224:225], v[224:225], 2, s[56:57]
	global_load_dword v226, v[224:225], off
	v_mul_lo_u32 v234, v234, 12
	v_add3_u32 v236, v234, v231, s81
	v_ashrrev_i32_e32 v237, 31, v236
	v_lshl_add_u64 v[236:237], v[236:237], 2, s[56:57]
	global_load_dword v238, v[236:237], off
	v_cmp_gt_i32_e32 vcc, s63, v2
	s_and_saveexec_b64 s[4:5], vcc
	s_cbranch_execz .LBB0_631
	v_lshl_add_u32 v0, v2, 2, 0
	s_mov_b64 s[6:7], 0
	v_mov_b32_e32 v3, v2
	s_branch .LBB0_629

.LBB0_1282:
	s_add_u32 s74, s26, 0xe200000
	s_addc_u32 s75, s27, 0
	s_add_u32 s76, s26, 0xe200c00
	s_addc_u32 s77, s27, 0
	s_add_u32 s34, s26, 0x5f00000
	s_addc_u32 s35, s27, 0
	s_add_u32 s78, s26, 0x22300000
	v_mbcnt_lo_u32_b32 v0, -1, 0
	s_addc_u32 s79, s27, 0
	s_movk_i32 s80, 0x82
	s_movk_i32 s81, 0xfdf8
	s_mov_b32 s82, 0x20000
	s_movk_i32 s83, 0xfe81
	s_movk_i32 s84, 0x1400
	v_mov_b32_e32 v169, 0
	v_mbcnt_hi_u32_b32 v181, -1, v0
	s_mov_b32 s85, 0xff61b1e6
	s_movk_i32 s86, 0x90
	s_movk_i32 s87, 0x80
	v_mov_b32_e32 v198, 0x100
	s_mov_b32 s88, 0xf0c9f2ca
	s_mov_b32 s89, 0x3e38aa3b
	s_movk_i32 s92, 0x4800
	v_mov_b32_e32 v199, 0xff61b1e6
	v_mov_b32_e32 v201, 0x7ff
	v_mov_b32_e32 v202, 0x10000
	v_mov_b32_e32 v203, 0xf149f2ca
	s_mov_b32 s93, s17
	s_waitcnt vmcnt(0)
	s_branch .LBB0_1284

.LBB0_1286:
	v_mov_b32_e32 v78, v200
	s_waitcnt lgkmcnt(0)
	v_cmp_gt_i32_e32 vcc, s80, v78
	s_barrier
	s_cmp_eq_u64 s[2:3], 0
	s_cbranch_scc1 .Lmoba_skipfill
	v_lshrrev_b32_e32 v236, 6, v200
	v_mul_u32_u24_e32 v236, 0xc00, v236
	v_and_b32_e32 v237, 63, v200
	v_lshl_add_u32 v236, v237, 2, v236
	v_mov_b32_e32 v237, 0
	v_lshl_add_u64 v[236:237], v[236:237], 0, s[50:51]
	v_lshl_add_u64 v[236:237], v[236:237], 0, s[34:35]
	global_load_dword v238, v[236:237], off
	v_add_u32_e32 v206, 0, v200
	v_min_u32_e32 v206, 703, v206
	v_cmp_lt_u32_e32 vcc, 703, v206
	v_mov_b32_e32 v213, 0
	s_nop 0
	v_cndmask_b32_e64 v207, 0, 1, vcc
	v_mul_u32_u24_e32 v208, 704, v207
	v_sub_u32_e32 v208, v206, v208
	v_subrev_u32_e32 v209, 96, v208
	v_max_i32_e32 v210, 0, v209
	v_min_i32_e32 v210, 0x80, v210
	v_lshlrev_b32_e32 v210, 2, v210
	v_add_u32_e32 v210, 0x20004, v210
	ds_read_b32 v210, v210
	v_mul_u32_u24_e32 v211, 0xb00, v207
	v_lshl_add_u32 v211, v208, 2, v211
	v_add_u32_e32 v211, 0x1d000, v211
	v_add_u32_e32 v218, 512, v200
	v_min_u32_e32 v218, 703, v218
	v_cmp_lt_u32_e32 vcc, 703, v218
	v_mov_b32_e32 v225, 0
	s_nop 0
	v_cndmask_b32_e64 v219, 0, 1, vcc
	v_mul_u32_u24_e32 v220, 704, v219
	v_sub_u32_e32 v220, v218, v220
	v_subrev_u32_e32 v221, 96, v220
	v_max_i32_e32 v222, 0, v221
	v_min_i32_e32 v222, 0x80, v222
	v_lshlrev_b32_e32 v222, 2, v222
	v_add_u32_e32 v222, 0x20004, v222
	ds_read_b32 v222, v222
	v_mul_u32_u24_e32 v223, 0xb00, v219
	v_lshl_add_u32 v223, v220, 2, v223
	v_add_u32_e32 v223, 0x1d000, v223
	s_waitcnt lgkmcnt(0)
	v_mul_lo_u32 v210, v210, 12
	v_add3_u32 v212, v210, v207, s94
	v_ashrrev_i32_e32 v213, 31, v212
	v_lshl_add_u64 v[212:213], v[212:213], 2, s[56:57]
	global_load_dword v214, v[212:213], off
	v_mul_lo_u32 v222, v222, 12
	v_add3_u32 v224, v222, v219, s94
	v_ashrrev_i32_e32 v225, 31, v224
	v_lshl_add_u64 v[224:225], v[224:225], 2, s[56:57]
	global_load_dword v226, v[224:225], off
	v_cmp_gt_i32_e32 vcc, s80, v78
	s_and_saveexec_b64 s[4:5], vcc
	s_cbranch_execz .LBB0_1291
	v_lshl_add_u32 v0, v78, 2, 0
	s_mov_b64 s[6:7], 0
	v_mov_b32_e32 v1, v78
	s_branch .LBB0_1289

.LBB0_1342:
	s_cmpk_gt_i32 s17, 0x1ff
	s_cbranch_scc1 .LBB0_1351
	s_add_u32 s4, s26, 0x22300000
	s_addc_u32 s5, s27, 0
	v_mbcnt_lo_u32_b32 v0, -1, 0
	s_add_u32 s0, s26, 0xe201200
	v_mbcnt_hi_u32_b32 v192, -1, v0
	s_addc_u32 s1, s27, 0
	v_and_b32_e32 v0, 64, v192
	s_mov_b32 s7, 0
	s_movk_i32 s12, 0x1400
	v_mov_b64_e32 v[168:169], s[0:1]
	v_mov_b32_e32 v171, 0
	s_mov_b64 s[8:9], 0x28000
	s_mov_b32 s13, 0x28000
	v_mov_b32_e32 v177, 0xff
	s_movk_i32 s14, 0x90
	s_mov_b32 s15, 0xf0c9f2ca
	s_mov_b32 s18, 0x3e38aa3b
	s_movk_i32 s19, 0x4800
	v_xor_b32_e32 v193, 32, v192
	v_add_u32_e32 v194, 64, v0
	s_waitcnt vmcnt(0)
	s_branch .LBB0_1345

.LBB0_1345:
	s_ashr_i32 s0, s17, 4
	s_ashr_i32 s1, s0, 31
	s_lshl_b64 s[2:3], s[0:1], 19
	s_add_u32 s2, s26, s2
	s_addc_u32 s3, s27, s3
	s_lshl_b32 s6, s17, 4
	s_and_b32 s20, s6, 0xc0
	s_lshl_b32 s6, s20, 1
	s_add_u32 s2, s2, s6
	s_addc_u32 s3, s3, 0
	s_add_u32 s2, s2, 0x4400400
	v_mov_b32_e32 v44, v200
	s_addc_u32 s3, s3, 0
	s_lshl_b32 s10, s17, 9
	s_and_b32 s10, s10, 0x600
	v_and_b32_e32 v0, 0xffffffc0, v44
	v_and_b32_e32 v45, 31, v44
	v_add_u32_e32 v0, s10, v0
	v_or_b32_e32 v0, v0, v45
	s_lshl_b64 s[0:1], s[0:1], 11
	v_ashrrev_i32_e32 v1, 31, v0
	v_lshl_add_u64 v[172:173], s[0:1], 0, v[0:1]
	v_mad_u64_u32 v[0:1], s[0:1], v172, s12, v[168:169]
	v_bfe_u32 v195, v44, 5, 1
	v_mad_i32_i24 v1, v173, s12, v1
	v_lshl_add_u64 v[0:1], v[0:1], 0, s[6:7]
	v_lshlrev_b32_e32 v170, 4, v195
	v_lshl_add_u64 v[32:33], v[0:1], 0, v[170:171]
	v_add_co_u32_e32 v36, vcc, s13, v32
	v_ashrrev_i32_e32 v198, 3, v44
	s_waitcnt lgkmcnt(0)
	s_barrier
	v_lshl_add_u64 v[34:35], v[32:33], 0, s[8:9]
	v_addc_co_u32_e32 v37, vcc, 0, v33, vcc
	global_load_dwordx4 v[0:3], v[32:33], off
	global_load_dwordx4 v[4:7], v[32:33], off offset:32
	global_load_dwordx4 v[8:11], v[34:35], off offset:32
	global_load_dwordx4 v[12:15], v[34:35], off offset:64
	global_load_dwordx4 v[16:19], v[32:33], off offset:64
	global_load_dwordx4 v[20:23], v[32:33], off offset:96
	global_load_dwordx4 v[24:27], v[36:37], off
	global_load_dwordx4 v[28:31], v[34:35], off offset:96
	v_med3_i32 v32, v198, 0, v177
	v_lshlrev_b32_e32 v32, 11, v32
	v_mov_b32_e32 v33, v171
	v_lshlrev_b32_e32 v34, 4, v44
	v_lshl_add_u64 v[32:33], s[2:3], 0, v[32:33]
	v_and_b32_e32 v40, 0x70, v34
	v_mov_b32_e32 v41, v171
	v_lshl_add_u64 v[42:43], v[32:33], 0, v[40:41]
	global_load_dwordx4 v[32:35], v[42:43], off
	global_load_dwordx4 v[36:39], v[42:43], off offset:512
	v_cmp_lt_i32_e32 vcc, v193, v194
	v_lshlrev_b32_e32 v43, 7, v44
	v_and_b32_e32 v43, 0xffffe000, v43
	v_cndmask_b32_e32 v42, v192, v193, vcc
	v_lshlrev_b32_e32 v196, 2, v42
	v_and_b32_e32 v42, 63, v44
	v_lshlrev_b32_e32 v42, 4, v42
	v_mul_lo_u32 v48, v198, s14
	v_add3_u32 v42, 0, v43, v42
	v_add3_u32 v176, 0, v48, v40
	v_mad_u64_u32 v[178:179], s[0:1], v198, 48, v[176:177]
	v_and_b32_e32 v46, 16, v44
	v_bfe_u32 v47, v44, 2, 2
	v_lshlrev_b32_e32 v44, 2, v44
	v_lshl_or_b32 v47, v195, 2, v47
	v_and_or_b32 v44, v44, 12, v46
	v_mul_u32_u24_e32 v45, 0x90, v45
	v_mul_u32_u24_e32 v43, 0xc0, v47
	v_add3_u32 v199, 0, v45, v170
	v_lshl_add_u64 v[180:181], s[2:3], 0, v[40:41]
	v_mov_b32_e32 v170, v171
	v_mov_b32_e32 v201, 0xf149f2ca
	s_mov_b32 s0, 64
	v_mov_b32_e32 v202, 0xf149f2ca
	s_mov_b32 s1, 0
	v_mov_b64_e32 v[174:175], v[170:171]
	s_waitcnt vmcnt(9)
	ds_write_b128 v42, v[0:3] offset:53248
	s_waitcnt vmcnt(8)
	ds_write_b128 v42, v[4:7] offset:54272
	s_waitcnt vmcnt(5)
	ds_write_b128 v42, v[16:19] offset:55296
	s_waitcnt vmcnt(4)
	ds_write_b128 v42, v[20:23] offset:56320
	s_waitcnt vmcnt(3)
	ds_write_b128 v42, v[24:27] offset:57344
	ds_write_b128 v42, v[8:11] offset:58368
	ds_write_b128 v42, v[12:15] offset:59392
	s_waitcnt vmcnt(2)
	ds_write_b128 v42, v[28:31] offset:60416
	s_waitcnt lgkmcnt(0)
	s_barrier
	s_waitcnt vmcnt(1)
	ds_write_b128 v176, v[32:35]
	s_waitcnt vmcnt(0)
	ds_write_b128 v178, v[36:39] offset:18432
	s_waitcnt lgkmcnt(0)
	s_barrier
	ds_read_b128 v[152:155], v42 offset:53248
	ds_read_b128 v[144:147], v42 offset:54272
	ds_read_b128 v[156:159], v42 offset:57344
	ds_read_b128 v[148:151], v42 offset:58368
	ds_read_b128 v[140:143], v42 offset:55296
	ds_read_b128 v[136:139], v42 offset:56320
	ds_read_b128 v[132:135], v42 offset:59392
	ds_read_b128 v[128:131], v42 offset:60416
	v_lshlrev_b32_e32 v0, 1, v44
	v_mov_b32_e32 v14, v171
	v_mov_b32_e32 v15, v171
	v_add3_u32 v179, 0, v43, v0
	v_mov_b32_e32 v0, v171
	v_mov_b32_e32 v1, v171
	v_mov_b32_e32 v2, v171
	v_mov_b32_e32 v3, v171
	v_mov_b32_e32 v4, v171
	v_mov_b32_e32 v5, v171
	v_mov_b32_e32 v6, v171
	v_mov_b32_e32 v7, v171
	v_mov_b32_e32 v8, v171
	v_mov_b32_e32 v9, v171
	v_mov_b32_e32 v10, v171
	v_mov_b32_e32 v11, v171
	v_mov_b32_e32 v12, v171
	v_mov_b32_e32 v13, v171
	v_mov_b64_e32 v[46:47], v[14:15]
	v_mov_b64_e32 v[62:63], v[14:15]
	v_mov_b64_e32 v[30:31], v[14:15]
	v_mov_b64_e32 v[44:45], v[12:13]
	v_mov_b64_e32 v[42:43], v[10:11]
	v_mov_b64_e32 v[40:41], v[8:9]
	v_mov_b64_e32 v[38:39], v[6:7]
	v_mov_b64_e32 v[36:37], v[4:5]
	v_mov_b64_e32 v[34:35], v[2:3]
	v_mov_b64_e32 v[32:33], v[0:1]
	v_mov_b64_e32 v[60:61], v[12:13]
	v_mov_b64_e32 v[58:59], v[10:11]
	v_mov_b64_e32 v[56:57], v[8:9]
	v_mov_b64_e32 v[54:55], v[6:7]
	v_mov_b64_e32 v[52:53], v[4:5]
	v_mov_b64_e32 v[50:51], v[2:3]
	v_mov_b64_e32 v[48:49], v[0:1]
	v_mov_b64_e32 v[28:29], v[12:13]
	v_mov_b64_e32 v[26:27], v[10:11]
	v_mov_b64_e32 v[24:25], v[8:9]
	v_mov_b64_e32 v[22:23], v[6:7]
	v_mov_b64_e32 v[20:21], v[4:5]
	v_mov_b64_e32 v[18:19], v[2:3]
	v_mov_b64_e32 v[16:17], v[0:1]
	s_branch .LBB0_1347
